# GLA tiles re-padded for ds_read_b128 (q rows 544 B, k^T and att rows 160 B) on top of the 12472 split
# speedup vs baseline: 1.0034x; 1.0034x over previous
; #define LAS __attribute__((address_space(3)))
;     __device__ __forceinline__ bf16* PROJ() const { return (bf16*)(ws + WS_PROJ); }
;     __device__ __forceinline__ float* DEC() const { return (float*)(ws + WS_DEC); }
;     __device__ __forceinline__ bf16* G012() const { return (bf16*)(ws + WS_WIN); }
;     __device__ __forceinline__ bf16* ATTG() const { return (bf16*)(ws + WS_ATTG); }
;     __device__ __forceinline__ bf16* G3() const { return (bf16*)((unsigned char*)out + OUT_G3); }
; __device__ __forceinline__ void p2b_gla_main(Frame& F) {
;     constexpr int QST = 528, KST = 144, VST = 144, AST = 144, OST = 272;
;     constexpr int L_QD = 0, L_KT = 64 * QST, L_V = L_KT + 256 * KST, L_ATT = L_V + 64 * VST, L_OP = L_ATT + 64 * AST, L_DEC = L_OP + 2 * 64 * OST, L_END = L_DEC + 1024;
;     static_assert(L_END <= RING_BYTES, "gla lds");
;     LAS unsigned char* lds = F.lds;
;     const int tid = F.tid, lane = F.lane, w = F.wave, cw = w & 3, kh = w >> 2, c16 = lane & 15, g = lane >> 4, q4 = (lane & 15) >> 2, p4 = lane & 3;
;     for (int unit = F.vcu; unit < BATCH * GH * 8; unit += F.G) {
;         const int b = unit >> 5, h = (unit >> 3) & 3, vs = unit & 7;
;         f32x4 S[8];
; #pragma unroll
;         for (int t = 0; t < 8; ++t) S[t] = (f32x4){0.f, 0.f, 0.f, 0.f};
;         v4u pq[4], pk[4], pv, pa; float pdec = 0.f;
;         v4u ngr, cgr; v2u ngb, cgb;
;         const bf16* gq0 = F.PROJ() + (size_t)b * SEQ * PW + C_GQ + h * GDK;
;         const bf16* gk0 = F.PROJ() + (size_t)b * SEQ * PW + C_GK + h * GDK;
;         const bf16* gv0 = F.PROJ() + (size_t)b * SEQ * PW + C_GV + h * GDV + vs * 64;
;         const bf16* ga0 = F.ATTG() + (size_t)(b * 32 * GH + h) * (64 * 64);
;         const int gpitch = (h < 3) ? 1536 : 512;
;         bf16* go0 = ((h < 3) ? F.G012() + h * GDV : F.G3()) + (size_t)b * SEQ * gpitch + vs * 64;
;         const float* dec0 = F.DEC() + (size_t)b * 32 * (GH * GDK) + h * GDK;
;         const bf16* gr0 = F.PROJ() + (size_t)b * SEQ * PW + C_GR + h * GDV + vs * 64 + (tid & 7) * 8;
;         float gwv[8];
;         { const f32x4 g0 = *(const f32x4*)(F.gnorm_w + vs * 64 + (tid & 7) * 8), g1 = *(const f32x4*)(F.gnorm_w + vs * 64 + (tid & 7) * 8 + 4);
;             gwv[0] = g0[0]; gwv[1] = g0[1]; gwv[2] = g0[2]; gwv[3] = g0[3]; gwv[4] = g1[0]; gwv[5] = g1[1]; gwv[6] = g1[2]; gwv[7] = g1[3]; }
.LBB0_538:
	s_cmp_lt_i32 s58, 4
	s_cselect_b64 s[0:1], -1, 0
	s_cmp_gt_i32 s59, 3
	s_cselect_b64 s[4:5], -1, 0
	s_and_b64 s[0:1], s[0:1], s[4:5]
	s_andn2_b64 vcc, exec, s[0:1]
	s_cbranch_vccnz .LBB0_610
	s_cmpk_gt_i32 s66, 0xff
	s_cbranch_scc1 .LBB0_557
	v_or_b32_e32 v1, 0x200, v0
	s_waitcnt vmcnt(0)
	v_lshrrev_b32_e32 v18, 5, v1
	v_or_b32_e32 v1, 0x600, v0
	s_bfe_u32 s8, s87, 0x20006
	v_lshrrev_b32_e32 v19, 5, v1
	v_and_b32_e32 v1, 31, v0
	v_lshlrev_b32_e32 v96, 4, v0
	v_lshlrev_b32_e32 v14, 3, v0
	v_lshlrev_b32_e32 v20, 4, v1
	v_and_b32_e32 v1, 0x70, v96
	s_add_i32 s6, 0, 0x12800
	s_lshl_b32 s9, s8, 5
	s_lshr_b32 s1, s87, 8
	v_and_b32_e32 v4, 0xf8, v14
	v_add_u32_e32 v22, 0, v1
	v_mov_b32_e32 v1, s6
	v_and_b32_e32 v14, 24, v14
	s_add_i32 s6, s6, s9
	v_lshrrev_b32_e32 v98, 3, v0
	s_movk_i32 s10, 0xa0
	s_movk_i32 s98, 0x90
	s_add_i32 s7, 0, 0x14c00
	v_add_u32_e32 v25, s6, v14
	s_lshl_b32 s6, s1, 6
	v_mad_u32_u24 v23, v98, s98, v1
	v_mov_b32_e32 v1, s7
	s_add_i32 s7, s7, s6
	v_and_b32_e32 v14, 48, v0
	s_cmpk_lt_u32 s87, 0x100
	v_add_u32_e32 v26, s7, v14
	s_cselect_b64 s[6:7], -1, 0
	s_and_b32 s9, s87, 0xffffff00
	s_add_i32 s9, s9, 0
	v_add_u32_e32 v27, s9, v14
	s_mul_i32 s9, s1, 0x4400
	s_add_i32 s12, 0, 0x17400
	s_add_i32 s9, s12, s9
	s_lshl_b32 s8, s8, 6
	v_and_b32_e32 v7, 15, v0
	s_add_i32 s9, s9, s8
	v_lshl_add_u32 v28, v7, 2, s9
	s_add_i32 s8, 0, 0x1fc00
	s_add_i32 s9, 0, 0x1b800
	v_lshrrev_b32_e32 v3, 5, v0
	v_bfe_u32 v15, v0, 3, 2
	v_add_u32_e32 v99, s8, v14
	s_movk_i32 s8, 0x110
	v_mov_b32_e32 v16, s9
	v_or_b32_e32 v5, 32, v3
	v_mad_u32_u24 v31, v98, s8, v16
	v_lshl_or_b32 v16, v3, 2, v15
	v_mul_u32_u24_e32 v8, 0x2a00, v5
	s_lshl_b32 s13, s1, 7
	v_mul_u32_u24_e32 v32, 0xa0, v16
	v_lshl_or_b32 v16, v18, 2, v15
	v_lshl_or_b32 v5, v5, 2, v15
	v_lshl_or_b32 v15, v19, 2, v15
	v_add_u32_e32 v29, 0, v14
	v_mov_b32_e32 v14, s12
	v_mul_u32_u24_e32 v36, 0xa0, v15
	v_or_b32_e32 v15, s13, v7
	s_or_b32 s12, s13, 16
	v_mul_lo_u32 v39, v15, s10
	v_or_b32_e32 v15, s12, v7
	s_lshl_b32 s34, s12, 2
	s_or_b32 s12, s13, 32
	v_mul_lo_u32 v40, v15, s10
	v_or_b32_e32 v15, s12, v7
	s_lshl_b32 s35, s12, 2
	s_or_b32 s12, s13, 48
	v_mul_lo_u32 v41, v15, s10
	v_or_b32_e32 v15, s12, v7
	s_lshl_b32 s36, s12, 2
	s_or_b32 s12, s13, 64
	v_mul_lo_u32 v42, v15, s10
	v_or_b32_e32 v15, s12, v7
	s_lshl_b32 s37, s12, 2
	s_or_b32 s12, s13, 0x50
	v_mul_lo_u32 v43, v15, s10
	v_or_b32_e32 v15, s12, v7
	s_lshl_b32 s38, s12, 2
	s_or_b32 s12, s13, 0x60
	v_and_b32_e32 v13, 7, v0
	v_mov_b32_e32 v97, 0
	v_mul_lo_u32 v44, v15, s10
	v_or_b32_e32 v15, s12, v7
	v_mad_u32_u24 v30, v98, s8, v14
	v_lshlrev_b32_e32 v14, 5, v13
	v_mul_lo_u32 v45, v15, s10
	v_mov_b32_e32 v15, v97
	s_lshl_b32 s39, s12, 2
	s_or_b32 s12, s13, 0x70
	v_lshl_add_u64 v[104:105], s[48:49], 0, v[14:15]
	v_mbcnt_lo_u32_b32 v15, -1, 0
	v_mul_u32_u24_e32 v34, 0xa0, v16
	v_mul_u32_u24_e32 v37, 0xa0, v7
	v_mul_u32_u24_e32 v38, 0x220, v7
	v_or_b32_e32 v7, s12, v7
	s_lshl_b32 s40, s12, 2
	v_lshl_add_u64 v[16:17], s[56:57], 0, v[96:97]
	s_mov_b64 s[12:13], 0x1ec00000
	v_mbcnt_hi_u32_b32 v15, -1, v15
	v_lshl_add_u64 v[106:107], v[16:17], 0, s[12:13]
	v_and_b32_e32 v17, 64, v15
	v_xor_b32_e32 v16, 1, v15
	v_add_u32_e32 v17, 64, v17
	v_cmp_lt_i32_e32 vcc, v16, v17
	s_lshl_b32 s1, s1, 9
	s_add_u32 s41, s56, 0x5c00000
	v_cndmask_b32_e32 v16, v15, v16, vcc
	v_lshlrev_b32_e32 v109, 2, v16
	v_xor_b32_e32 v16, 2, v15
	s_addc_u32 s42, s57, 0
	v_cmp_lt_i32_e32 vcc, v16, v17
	s_add_u32 s43, s56, 0x2800000
	s_addc_u32 s44, s57, 0
	v_cndmask_b32_e32 v16, v15, v16, vcc
	v_lshlrev_b32_e32 v160, 2, v16
	v_xor_b32_e32 v16, 4, v15
	s_add_u32 s45, s54, 0x6c00000
	v_cmp_lt_i32_e32 vcc, v16, v17
	s_addc_u32 s50, s55, 0
	v_bfe_u32 v9, v0, 2, 2
	v_cndmask_b32_e32 v15, v15, v16, vcc
	v_lshrrev_b32_e32 v11, 4, v183
	v_lshlrev_b32_e32 v94, 3, v13
	v_mul_u32_u24_e32 v2, 0x2a00, v3
	v_lshlrev_b32_e32 v100, 4, v13
	v_cmp_eq_u32_e64 s[8:9], 0, v13
	v_mul_u32_u24_e32 v13, 0x220, v3
	s_add_u32 s51, s56, 0x300000
	v_lshlrev_b32_e32 v161, 2, v15
	v_mov_b32_e32 v15, 0x400000
	v_mul_hi_u32_u24_e32 v115, 0x5400, v3
	v_mul_u32_u24_e32 v3, 0x5400, v3
	v_lshl_or_b32 v9, v11, 3, v9
	s_addc_u32 s63, s57, 0
	v_lshl_or_b32 v110, v98, 7, v15
	v_mul_u32_u24_e32 v15, 0x5400, v19
	v_or_b32_e32 v114, v3, v20
	v_mul_hi_u32_u24_e32 v117, 0x5400, v98
	v_mul_u32_u24_e32 v3, 0x5400, v98
	v_mul_u32_u24_e32 v6, 0x2a00, v18
	v_mul_u32_u24_e32 v10, 0x2a00, v19
	v_mul_u32_u24_e32 v12, 0x2a00, v98
	s_movk_i32 s4, 0x100
	v_add_u32_e32 v21, 0, v20
	v_mad_u32_u24 v24, v98, s10, v1
	v_lshlrev_b32_e32 v1, 2, v0
	v_mul_u32_u24_e32 v33, 0x220, v18
	v_mul_u32_u24_e32 v5, 0xa0, v5
	v_mul_u32_u24_e32 v35, 0x220, v19
	v_mul_u32_u24_e32 v9, 0x90, v9
	v_mul_u32_u24_e32 v11, 0x440, v11
	v_mul_lo_u32 v7, v7, s10
	s_add_u32 s12, s56, 0x400000
	v_or_b32_e32 v112, v15, v20
	v_mul_u32_u24_e32 v15, 0x5400, v18
	v_or_b32_e32 v16, v3, v94
	v_mov_b32_e32 v17, v117
	s_mov_b64 s[14:15], 0x5d54c00
	v_mov_b32_e32 v95, v97
	s_movk_i32 s0, 0x600
	v_cmp_gt_u32_e64 s[4:5], s4, v0
	s_mov_b32 s11, 0
	v_or_b32_e32 v102, 0x7c0, v98
	v_mov_b32_e32 v103, v97
	s_addc_u32 s13, s57, 0
	v_mov_b32_e32 v101, v97
	v_lshlrev_b32_e32 v108, 1, v98
	v_mov_b32_e32 v111, v97
	s_movk_i32 s48, 0x5400
	v_mul_hi_u32_u24_e32 v113, 0x5400, v19
	v_or_b32_e32 v116, v3, v100
	v_mul_hi_u32_u24_e32 v119, 0x5400, v18
	v_or_b32_e32 v118, v15, v20
	v_or_b32_e32 v120, 0x301000, v1
	v_mov_b32_e32 v121, v97
	v_or_b32_e32 v122, 0x1ec08000, v96
	v_mov_b32_e32 v123, v97
	s_lshl_b32 s49, s66, 2
	s_lshl_b32 s64, s62, 2
	v_lshl_add_u64 v[124:125], v[16:17], 0, s[14:15]
	s_movk_i32 s65, 0xff80
	v_lshlrev_b32_e32 v126, 1, v2
	v_lshlrev_b32_e32 v128, 1, v4
	v_lshlrev_b32_e32 v130, 1, v6
	v_lshlrev_b32_e32 v132, 1, v8
	v_lshlrev_b32_e32 v134, 1, v10
	v_lshlrev_b32_e32 v136, 1, v12
	s_movk_i32 s67, 0x2000
	s_movk_i32 s68, 0x3000
	v_lshlrev_b32_e32 v162, 2, v0
	s_mov_b32 s69, 0x5d52000
	s_mov_b32 s70, 0x5d51000
	s_mov_b32 s71, 0x5df9000
	v_add_u32_e32 v163, v29, v39
	v_add_u32_e32 v164, v29, v40
	v_add_u32_e32 v165, v29, v41
	v_add_u32_e32 v166, v29, v42
	v_add_u32_e32 v167, v29, v43
	v_add_u32_e32 v168, v29, v44
	v_add_u32_e32 v169, v29, v45
	v_add_u32_e32 v170, v29, v7
	s_mov_b64 s[14:15], 0x2000
	s_mov_b64 s[16:17], 0x150000
	s_mov_b64 s[18:19], 0x1000
	s_mov_b64 s[20:21], 0x8000
	v_lshlrev_b32_e32 v96, 1, v94
	v_mov_b32_e32 v171, 0x5400
	v_add_u32_e32 v172, v21, v13
	v_add_u32_e32 v173, v22, v32
	v_add_u32_e32 v174, v21, v33
	v_add_u32_e32 v175, v22, v34
	v_add_u32_e32 v176, v22, v5
	v_add_u32_e32 v177, v21, v35
	v_add_u32_e32 v178, v22, v36
	v_add_u32_e32 v179, v23, v100
	v_add_u32_e32 v180, v24, v100
	v_add_u32_e32 v181, v25, v9
	v_add_u32_e32 v182, v26, v37
	v_add_u32_e32 v184, v27, v38
	v_add_u32_e32 v185, v28, v11
	v_add_u32_e32 v186, v30, v14
	v_add_u32_e32 v187, v31, v14
	s_mov_b32 s72, s66
	s_mov_b32 s73, s66
	s_branch .LBB0_542

.LBB0_544:
	s_or_b64 exec, exec, s[26:27]
	s_waitcnt vmcnt(11)
	ds_write_b128 v172, v[10:13]
	s_waitcnt vmcnt(10)
	ds_write_b128 v173, v[18:21] offset:34816
	s_waitcnt vmcnt(9)
	ds_write_b128 v174, v[22:25]
	s_waitcnt vmcnt(8)
	ds_write_b128 v175, v[26:29] offset:34816
	s_waitcnt vmcnt(7)
	ds_write_b128 v172, v[30:33] offset:17408
	s_waitcnt vmcnt(6)
	ds_write_b128 v176, v[34:37] offset:34816
	s_waitcnt vmcnt(5)
	ds_write_b128 v177, v[38:41]
	s_waitcnt vmcnt(4)
	ds_write_b128 v178, v[42:45] offset:34816
	s_waitcnt vmcnt(3)
	ds_write_b128 v179, v[46:49]
	s_waitcnt vmcnt(2)
	ds_write_b128 v180, v[50:53]
	v_add_u32_e32 v10, 0, v1
	v_add_u32_e32 v129, 0x1fc00, v10
	s_and_saveexec_b64 s[26:27], s[4:5]
	s_cbranch_execz .LBB0_546
	s_waitcnt vmcnt(0)
	ds_write_b32 v129, v127

; #define LAS __attribute__((address_space(3)))
; __device__ __forceinline__ void p2b_gla_main(Frame& F) {
;     ...
;             bf16x8_t vf[2];
; #pragma unroll
;             for (int s = 0; s < 2; ++s) { const LAS unsigned char* vp = lds + L_V + (32 * s + 8 * g + q4) * VST + (16 * cw + 4 * p4) * 2; vf[s] = cat8(tr_read(vp), tr_read(vp + 4 * VST)); }
;             bf16x8_t sb[4];
; #pragma unroll
;             for (int s = 0; s < 4; ++s) { v4u t; t.x = cvtpk(S[2 * s][0], S[2 * s][1]); t.y = cvtpk(S[2 * s][2], S[2 * s][3]); t.z = cvtpk(S[2 * s + 1][0], S[2 * s + 1][1]); t.w = cvtpk(S[2 * s + 1][2], S[2 * s + 1][3]); sb[s] = __builtin_bit_cast(bf16x8_t, t); }
;             float gs[8];
; #pragma unroll
;             for (int j = 0; j < 4; ++j) { const unsigned wj = cgr[j]; const float x0 = bflo(wj), x1 = bfhi(wj);
;                 const unsigned wb_ = (j < 2) ? cgb.x : cgb.y; const int sh = 16 * (j & 1);
;                 const float b0 = ((float)((wb_ >> sh) & 0xffu) - 128.f) * 0.03125f, b1 = ((float)((wb_ >> (sh + 8)) & 0xffu) - 128.f) * 0.03125f;
;                 gs[2 * j] = gwv[2 * j] * x0 * __builtin_amdgcn_rcpf((1.0f + __builtin_amdgcn_exp2f(-1.4426950408889634f * x0)) * (1.0f + __builtin_amdgcn_exp2f(-1.4426950408889634f * b0)));
;                 gs[2 * j + 1] = gwv[2 * j + 1] * x1 * __builtin_amdgcn_rcpf((1.0f + __builtin_amdgcn_exp2f(-1.4426950408889634f * x1)) * (1.0f + __builtin_amdgcn_exp2f(-1.4426950408889634f * b1))); }
; #pragma unroll
;             for (int it = 0; it < 4; ++it) {
;                 f32x4 oa = {0.f, 0.f, 0.f, 0.f};
;                 { const bf16x8_t a = *(const LAS bf16x8_t*)(lds + L_ATT + (16 * it + c16) * AST + (32 * kh + 8 * g) * 2); oa = MFMA16(a, kh ? vf[1] : vf[0], oa); }
;                 const LAS unsigned char* qp = lds + L_QD + (16 * it + c16) * QST + (128 * kh) * 2 + g * 16;
; #pragma unroll
;                 for (int s = 0; s < 4; ++s) oa = MFMA16(*(const LAS bf16x8_t*)(qp + s * 64), sb[s], oa);
; #pragma unroll
;                 for (int r = 0; r < 4; ++r) *(LAS float*)(lds + L_OP + kh * 64 * OST + (16 * it + 4 * g + r) * OST + (16 * cw + c16) * 4) = oa[r];
;                 if (c + 1 < SEQ / GCHUNK) GLA_LOAD_QK(c + 1, it);
;             }
; #pragma unroll
;             for (int t = 0; t < 8; ++t) {
;                 const LAS unsigned char* kp = lds + L_KT + (128 * kh + 16 * t + c16) * KST + g * 16;
; #pragma unroll
.LBB0_549:
	s_or_b64 exec, exec, s[28:29]
	ds_read_b64_tr_b16 v[62:63], v181
	ds_read_b64_tr_b16 v[64:65], v181 offset:576
	ds_read_b64_tr_b16 v[90:91], v181 offset:4608
	ds_read_b64_tr_b16 v[92:93], v181 offset:5184
	ds_read_b128 v[66:69], v182
	ds_read_b128 v[78:81], v184
	ds_read_b128 v[82:85], v184 offset:64
	ds_read_b128 v[86:89], v184 offset:128
	s_waitcnt lgkmcnt(4)
	v_cndmask_b32_e64 v77, v93, v65, s[6:7]
	v_cndmask_b32_e64 v76, v92, v64, s[6:7]
	v_cndmask_b32_e64 v75, v91, v63, s[6:7]
	v_cndmask_b32_e64 v74, v90, v62, s[6:7]
	v_cvt_pk_bf16_f32 v58, v42, v43
	v_cvt_pk_bf16_f32 v59, v44, v45
	s_waitcnt lgkmcnt(3)
	v_mfma_f32_16x16x32_bf16 v[66:69], v[66:69], v[74:77], 0
	v_cvt_pk_bf16_f32 v60, v46, v47
	v_cvt_pk_bf16_f32 v61, v48, v49
	v_cvt_pk_bf16_f32 v70, v34, v35
	v_cvt_pk_bf16_f32 v71, v36, v37
	s_waitcnt lgkmcnt(2)
	v_mfma_f32_16x16x32_bf16 v[66:69], v[78:81], v[58:61], v[66:69]
	v_cvt_pk_bf16_f32 v72, v26, v27
	v_cvt_pk_bf16_f32 v73, v28, v29
	ds_read_b128 v[188:191], v184 offset:192
	v_cvt_pk_bf16_f32 v78, v30, v31
	s_waitcnt lgkmcnt(2)
	v_mfma_f32_16x16x32_bf16 v[66:69], v[82:85], v[70:73], v[66:69]
	v_cvt_pk_bf16_f32 v79, v32, v33
	v_cvt_pk_bf16_f32 v80, v38, v39
	v_cvt_pk_bf16_f32 v81, v40, v41
	v_cvt_pk_bf16_f32 v82, v18, v19
	v_cvt_pk_bf16_f32 v83, v20, v21
	s_waitcnt lgkmcnt(1)
	v_mfma_f32_16x16x32_bf16 v[66:69], v[86:89], v[78:81], v[66:69]
	v_cvt_pk_bf16_f32 v84, v22, v23
	v_cvt_pk_bf16_f32 v85, v24, v25
	v_add_u32_e32 v135, 0x2000, v185
	v_add_u32_e32 v137, 0x2400, v185
	s_waitcnt lgkmcnt(0)
	v_mfma_f32_16x16x32_bf16 v[66:69], v[188:191], v[82:85], v[66:69]
	s_nop 7
	ds_write2_b32 v185, v66, v67 offset1:68
	ds_write2_b32 v185, v68, v69 offset0:136 offset1:204
	ds_read_b128 v[66:69], v182 offset:2560
	ds_read_b128 v[86:89], v184 offset:8704
	s_waitcnt lgkmcnt(1)
	v_mfma_f32_16x16x32_bf16 v[66:69], v[66:69], v[74:77], 0
	ds_read_b128 v[188:191], v184 offset:8768
	v_add_u32_e32 v131, 0x3200, v185
	v_add_u32_e32 v133, 0x3400, v185
	s_waitcnt lgkmcnt(1)
	v_mfma_f32_16x16x32_bf16 v[66:69], v[86:89], v[58:61], v[66:69]
	ds_read_b128 v[86:89], v184 offset:8832
	v_add_u32_e32 v214, s34, v99
	s_waitcnt lgkmcnt(1)
	v_mfma_f32_16x16x32_bf16 v[66:69], v[188:191], v[70:73], v[66:69]
	v_add_u32_e32 v188, 0x1000, v185
	v_add_u32_e32 v189, 0x1200, v185
	s_waitcnt lgkmcnt(0)
	v_mfma_f32_16x16x32_bf16 v[66:69], v[86:89], v[78:81], v[66:69]
	ds_read_b128 v[86:89], v184 offset:8896
	s_waitcnt lgkmcnt(0)
	v_mfma_f32_16x16x32_bf16 v[66:69], v[86:89], v[82:85], v[66:69]
	s_nop 7
	ds_write2_b32 v188, v66, v67 offset0:64 offset1:132
	ds_write2_b32 v189, v68, v69 offset0:72 offset1:140
	ds_read_b128 v[66:69], v182 offset:5120
	ds_read_b128 v[86:89], v184 offset:17408
	s_waitcnt lgkmcnt(1)
	v_mfma_f32_16x16x32_bf16 v[66:69], v[66:69], v[74:77], 0
	ds_read_b128 v[190:193], v184 offset:17472
	s_waitcnt lgkmcnt(1)
	v_mfma_f32_16x16x32_bf16 v[66:69], v[86:89], v[58:61], v[66:69]
	ds_read_b128 v[86:89], v184 offset:17536
	s_waitcnt lgkmcnt(1)
	v_mfma_f32_16x16x32_bf16 v[66:69], v[190:193], v[70:73], v[66:69]
	v_lshl_add_u64 v[190:191], s[56:57], 0, v[146:147]
	s_waitcnt lgkmcnt(0)
	v_mfma_f32_16x16x32_bf16 v[66:69], v[86:89], v[78:81], v[66:69]
	ds_read_b128 v[86:89], v184 offset:17600
	s_waitcnt lgkmcnt(0)
	v_mfma_f32_16x16x32_bf16 v[66:69], v[86:89], v[82:85], v[66:69]
	s_nop 7
	ds_write2_b32 v135, v66, v67 offset0:128 offset1:196
	ds_write2_b32 v137, v68, v69 offset0:8 offset1:76
	ds_read_b128 v[66:69], v182 offset:7680
	ds_read_b128 v[86:89], v184 offset:26112
	s_waitcnt lgkmcnt(1)
	v_mfma_f32_16x16x32_bf16 v[66:69], v[66:69], v[74:77], 0
	ds_read_b128 v[74:77], v184 offset:26176
	s_waitcnt lgkmcnt(1)
	v_mfma_f32_16x16x32_bf16 v[58:61], v[86:89], v[58:61], v[66:69]
	v_lshl_add_u64 v[86:87], s[56:57], 0, v[148:149]
	v_add_co_u32_e32 v194, vcc, s70, v86
	s_nop 2
	ds_read_b128 v[66:69], v184 offset:26240
	s_waitcnt lgkmcnt(1)
	v_mfma_f32_16x16x32_bf16 v[58:61], v[74:77], v[70:73], v[58:61]
	v_addc_co_u32_e32 v195, vcc, 0, v87, vcc
	s_waitcnt lgkmcnt(0)
	v_mfma_f32_16x16x32_bf16 v[58:61], v[66:69], v[78:81], v[58:61]
	ds_read_b128 v[66:69], v184 offset:26304
	s_waitcnt lgkmcnt(0)
	v_mfma_f32_16x16x32_bf16 v[58:61], v[66:69], v[82:85], v[58:61]
	s_nop 7
	ds_write2_b32 v131, v58, v59 offset0:64 offset1:132
	ds_write2_b32 v133, v60, v61 offset0:72 offset1:140
	ds_read_b128 v[58:61], v163 offset:34816
	ds_read_b128 v[66:69], v164 offset:34816
	v_lshl_add_u64 v[82:83], s[56:57], 0, v[152:153]
	ds_read_b128 v[70:73], v163 offset:34880
	ds_read_b128 v[74:77], v165 offset:34816
	s_waitcnt lgkmcnt(3)
	v_mfma_f32_16x16x32_bf16 v[42:45], v[58:61], v[62:65], v[42:45]
	v_add_co_u32_e32 v202, vcc, s70, v82
	s_waitcnt lgkmcnt(2)
	v_mfma_f32_16x16x32_bf16 v[58:61], v[66:69], v[62:65], v[46:49]
	s_nop 2
	ds_read_b128 v[46:49], v166 offset:34816
	ds_read_b128 v[66:69], v165 offset:34880
	ds_read_b128 v[78:81], v167 offset:34816
	v_addc_co_u32_e32 v203, vcc, 0, v83, vcc
	s_waitcnt lgkmcnt(2)
	v_mfma_f32_16x16x32_bf16 v[82:85], v[46:49], v[62:65], v[26:29]
	v_add_co_u32_e32 v46, vcc, s71, v86
	s_nop 1
	v_addc_co_u32_e32 v47, vcc, 0, v87, vcc
	v_add_co_u32_e32 v218, vcc, s70, v190
	v_mfma_f32_16x16x32_bf16 v[34:37], v[74:77], v[62:65], v[34:37]
	s_nop 0
	v_addc_co_u32_e32 v219, vcc, 0, v191, vcc
	ds_read_b128 v[74:77], v168 offset:34816
	ds_read_b128 v[86:89], v167 offset:34880
	ds_read_b128 v[26:29], v164 offset:34880
	global_load_dwordx4 v[190:193], v[194:195], off offset:1024
	s_nop 0
	global_load_dwordx4 v[194:197], v[194:195], off offset:3072
	s_nop 0
	global_load_dwordx4 v[198:201], v[202:203], off offset:1024
	s_nop 0
	global_load_dwordx4 v[202:205], v[202:203], off offset:3072
	s_nop 0
	global_load_dwordx4 v[206:209], v[46:47], off offset:1024
	global_load_dwordx4 v[210:213], v[46:47], off offset:3072
	ds_read_b128 v[46:49], v214
	global_load_dwordx4 v[214:217], v[218:219], off offset:1024
	s_nop 0
	global_load_dwordx4 v[218:221], v[218:219], off offset:3072
	s_waitcnt lgkmcnt(4)
; #define LAS __attribute__((address_space(3)))
; #define MFMA16(a, b, c) __builtin_amdgcn_mfma_f32_16x16x32_bf16((a), (b), (c), 0, 0, 0)
; __device__ __forceinline__ void p2b_gla_main(Frame& F) {
;     ...
; #pragma unroll
;             for (int t = 0; t < 8; ++t) {
;                 const LAS unsigned char* kp = lds + L_KT + (128 * kh + 16 * t + c16) * KST + g * 16;
; #pragma unroll
;                 for (int s = 0; s < 2; ++s) S[t] = MFMA16(*(const LAS bf16x8_t*)(kp + s * 64), vf[s], S[t]);
;                 const f32x4 dc = *(const LAS f32x4*)(lds + L_DEC + (128 * kh + 16 * t + 4 * g) * 4);
;                 S[t] = S[t] * dc;
;             }
	v_mfma_f32_16x16x32_bf16 v[30:33], v[78:81], v[62:65], v[30:33]
	s_waitcnt lgkmcnt(3)
	v_mfma_f32_16x16x32_bf16 v[78:81], v[74:77], v[62:65], v[38:41]
	s_nop 2
	ds_read_b128 v[38:41], v166 offset:34880
	s_waitcnt lgkmcnt(2)
	v_mfma_f32_16x16x32_bf16 v[74:77], v[26:29], v[90:93], v[58:61]
	v_add_u32_e32 v26, s36, v99
	ds_read_b128 v[26:29], v26
	v_mfma_f32_16x16x32_bf16 v[34:37], v[66:69], v[90:93], v[34:37]
	ds_read_b128 v[58:61], v168 offset:34880
	ds_read_b128 v[66:69], v169 offset:34816
	v_mfma_f32_16x16x32_bf16 v[42:45], v[70:73], v[90:93], v[42:45]
	s_waitcnt lgkmcnt(3)
	v_mfma_f32_16x16x32_bf16 v[70:73], v[38:41], v[90:93], v[82:85]
	v_add_u32_e32 v38, s38, v99
	ds_read_b128 v[38:41], v38
	ds_read_b128 v[222:225], v169 offset:34880
	s_waitcnt lgkmcnt(3)
	v_mfma_f32_16x16x32_bf16 v[58:61], v[58:61], v[90:93], v[78:81]
	s_nop 2
	v_add_u32_e32 v78, s1, v99
	v_mfma_f32_16x16x32_bf16 v[30:33], v[86:89], v[90:93], v[30:33]
	ds_read_b128 v[86:89], v78
	ds_read_b128 v[226:229], v170 offset:34816
	s_waitcnt lgkmcnt(4)
	v_mfma_f32_16x16x32_bf16 v[18:21], v[66:69], v[62:65], v[18:21]
	v_add_u32_e32 v66, s35, v99
	ds_read_b128 v[82:85], v66
	ds_read_b128 v[230:233], v170 offset:34880
	v_add_u32_e32 v66, s37, v99
	s_waitcnt lgkmcnt(2)
	v_mfma_f32_16x16x32_bf16 v[62:65], v[226:229], v[62:65], v[22:25]
	ds_read_b128 v[78:81], v66
	s_nop 1
	v_add_u32_e32 v22, s40, v99
	ds_read_b128 v[22:25], v22
	v_add_u32_e32 v66, s39, v99
	ds_read_b128 v[66:69], v66
	v_mfma_f32_16x16x32_bf16 v[18:21], v[222:225], v[90:93], v[18:21]
	s_waitcnt lgkmcnt(0)
	s_barrier
; #define LAS __attribute__((address_space(3)))
;     __device__ __forceinline__ float* SSQG() const { return (float*)(ws + WS_SSQG); }
; #define GLA_TICK(sec) do { if (blockIdx.x == 0 && F.wave == 0) { const unsigned tn_ = (unsigned)__builtin_amdgcn_s_memrealtime(); if ((sec) == PROBE_KIND) F.MISC[60] += tn_ - F.MISC[61]; F.MISC[61] = tn_; } } while (0)
; #define GLA_TICK(sec) do { } while (0)
; __device__ __forceinline__ void p2b_gla_main(Frame& F) {
;     ...
;             float gs[8];
; #pragma unroll
;             for (int j = 0; j < 4; ++j) { const unsigned wj = cgr[j]; const float x0 = bflo(wj), x1 = bfhi(wj);
;                 const unsigned wb_ = (j < 2) ? cgb.x : cgb.y; const int sh = 16 * (j & 1);
;                 const float b0 = ((float)((wb_ >> sh) & 0xffu) - 128.f) * 0.03125f, b1 = ((float)((wb_ >> (sh + 8)) & 0xffu) - 128.f) * 0.03125f;
;                 gs[2 * j] = gwv[2 * j] * x0 * __builtin_amdgcn_rcpf((1.0f + __builtin_amdgcn_exp2f(-1.4426950408889634f * x0)) * (1.0f + __builtin_amdgcn_exp2f(-1.4426950408889634f * b0)));
;                 gs[2 * j + 1] = gwv[2 * j + 1] * x1 * __builtin_amdgcn_rcpf((1.0f + __builtin_amdgcn_exp2f(-1.4426950408889634f * x1)) * (1.0f + __builtin_amdgcn_exp2f(-1.4426950408889634f * b1))); }
;     ...
;             __syncthreads();
;             GLA_TICK(7);
;             if (c + 1 < SEQ / GCHUNK) GLA_STORE();
;             { const int row = tid >> 3, cg = tid & 7;
;                 const LAS f32x4* o0 = (const LAS f32x4*)(lds + L_OP + row * OST + cg * 32); const LAS f32x4* o1 = (const LAS f32x4*)(lds + L_OP + 64 * OST + row * OST + cg * 32);
;                 const f32x4 a = o0[0] + o1[0], bq = o0[1] + o1[1];
;                 v4u wv; wv.x = cvtpk(a[0] * gs[0], a[1] * gs[1]); wv.y = cvtpk(a[2] * gs[2], a[3] * gs[3]); wv.z = cvtpk(bq[0] * gs[4], bq[1] * gs[5]); wv.w = cvtpk(bq[2] * gs[6], bq[3] * gs[7]);
;                 const size_t grow = (size_t)c * GCHUNK + row;
;                 *(v4u*)(go0 + grow * gpitch + cg * 8) = wv;
;                 float ss = (a[0] * a[0] + a[1] * a[1]) + (a[2] * a[2] + a[3] * a[3]) + (bq[0] * bq[0] + bq[1] * bq[1]) + (bq[2] * bq[2] + bq[3] * bq[3]);
;                 ss += __shfl_xor(ss, 1); ss += __shfl_xor(ss, 2); ss += __shfl_xor(ss, 4);
;                 if (cg == 0) F.SSQG()[((size_t)b * SEQ + grow) * 32 + h * 8 + vs] = ss; }
	v_mfma_f32_16x16x32_bf16 v[62:65], v[230:233], v[90:93], v[62:65]
	s_waitcnt vmcnt(7)
	ds_write_b128 v172, v[190:193]
	s_waitcnt vmcnt(6)
	ds_write_b128 v173, v[194:197] offset:34816
	s_waitcnt vmcnt(5)
	ds_write_b128 v174, v[198:201]
	s_waitcnt vmcnt(4)
	ds_write_b128 v175, v[202:205] offset:34816
	s_waitcnt vmcnt(3)
	ds_write_b128 v172, v[206:209] offset:17408
	s_waitcnt vmcnt(2)
	ds_write_b128 v176, v[210:213] offset:34816
	s_waitcnt vmcnt(1)
	ds_write_b128 v177, v[214:217]
	s_waitcnt vmcnt(0)
	ds_write_b128 v178, v[218:221] offset:34816
	ds_write_b128 v179, v[50:53]
	ds_write_b128 v180, v[54:57]
	s_and_saveexec_b64 s[28:29], s[4:5]
	ds_write_b32 v129, v127
	s_or_b64 exec, exec, s[28:29]
	v_add_u32_sdwa v50, v158, s65 dst_sel:DWORD dst_unused:UNUSED_PAD src0_sel:BYTE_0 src1_sel:DWORD
	v_cvt_f32_i32_e32 v50, v50
	v_add_u32_sdwa v51, v158, s65 dst_sel:DWORD dst_unused:UNUSED_PAD src0_sel:BYTE_1 src1_sel:DWORD
	v_cvt_f32_i32_e32 v51, v51
	v_lshlrev_b32_e32 v52, 16, v14
	v_mul_f32_e32 v50, 0x3d000000, v50
	v_mul_f32_e32 v50, 0xbfb8aa3b, v50
	v_and_b32_e32 v53, 0xffff0000, v14
	v_mul_f32_e32 v14, 0xbfb8aa3b, v52
	v_mul_f32_e32 v55, 0x3d000000, v51
	v_exp_f32_e32 v51, v50
	v_exp_f32_e32 v50, v14
	v_mul_f32_e32 v14, 0xbfb8aa3b, v53
	v_exp_f32_e32 v54, v14
	v_mul_f32_e32 v14, 0xbfb8aa3b, v55
	v_pk_add_f32 v[50:51], v[50:51], 1.0 op_sel_hi:[1,0]
	v_exp_f32_e32 v55, v14
	v_mul_f32_e32 v14, v50, v51
	v_rcp_f32_e32 v50, v14
	v_add_u32_sdwa v14, v158, s65 dst_sel:DWORD dst_unused:UNUSED_PAD src0_sel:BYTE_2 src1_sel:DWORD
	v_cvt_f32_i32_e32 v14, v14
	v_add_u32_sdwa v51, v158, s65 dst_sel:DWORD dst_unused:UNUSED_PAD src0_sel:BYTE_3 src1_sel:DWORD
	v_cvt_f32_i32_e32 v56, v51
	v_pk_add_f32 v[54:55], v[54:55], 1.0 op_sel_hi:[1,0]
	v_mul_f32_e32 v14, 0x3d000000, v14
	v_mul_f32_e32 v14, 0xbfb8aa3b, v14
	v_mul_f32_e32 v51, v54, v55
	v_exp_f32_e32 v55, v14
	v_lshlrev_b32_e32 v14, 16, v15
	v_mul_f32_e32 v54, 0xbfb8aa3b, v14
	v_mul_f32_e32 v57, 0x3d000000, v56
	v_and_b32_e32 v15, 0xffff0000, v15
	v_exp_f32_e32 v54, v54
	v_mul_f32_e32 v56, 0xbfb8aa3b, v15
	v_mul_f32_e32 v57, 0xbfb8aa3b, v57
	v_exp_f32_e32 v56, v56
	v_exp_f32_e32 v57, v57
	v_pk_add_f32 v[54:55], v[54:55], 1.0 op_sel_hi:[1,0]
	v_lshlrev_b32_e32 v192, 16, v16
	v_mul_f32_e32 v54, v54, v55
	v_rcp_f32_e32 v190, v54
	v_pk_add_f32 v[54:55], v[56:57], 1.0 op_sel_hi:[1,0]
	v_add_u32_sdwa v56, v159, s65 dst_sel:DWORD dst_unused:UNUSED_PAD src0_sel:BYTE_0 src1_sel:DWORD
	v_cvt_f32_i32_e32 v56, v56
	v_add_u32_sdwa v57, v159, s65 dst_sel:DWORD dst_unused:UNUSED_PAD src0_sel:BYTE_1 src1_sel:DWORD
	v_mul_f32_e32 v54, v54, v55
	v_cvt_f32_i32_e32 v57, v57
	v_rcp_f32_e32 v191, v54
	v_mul_f32_e32 v54, 0x3d000000, v56
	v_mul_f32_e32 v54, 0xbfb8aa3b, v54
	v_and_b32_e32 v193, 0xffff0000, v16
	v_mul_f32_e32 v16, 0xbfb8aa3b, v192
	v_exp_f32_e32 v55, v54
	v_exp_f32_e32 v54, v16
	v_mul_f32_e32 v57, 0x3d000000, v57
	v_mul_f32_e32 v16, 0xbfb8aa3b, v193
	v_exp_f32_e32 v56, v16
	v_mul_f32_e32 v16, 0xbfb8aa3b, v57
	v_exp_f32_e32 v57, v16
	v_pk_add_f32 v[54:55], v[54:55], 1.0 op_sel_hi:[1,0]
	v_lshlrev_b32_e32 v194, 16, v17
	v_mul_f32_e32 v16, v54, v55
	v_rcp_f32_e32 v158, v16
	v_add_u32_sdwa v16, v159, s65 dst_sel:DWORD dst_unused:UNUSED_PAD src0_sel:BYTE_2 src1_sel:DWORD
	v_cvt_f32_i32_e32 v16, v16
	v_pk_add_f32 v[54:55], v[56:57], 1.0 op_sel_hi:[1,0]
	v_add_u32_sdwa v56, v159, s65 dst_sel:DWORD dst_unused:UNUSED_PAD src0_sel:BYTE_3 src1_sel:DWORD
	v_cvt_f32_i32_e32 v56, v56
	v_mul_f32_e32 v16, 0x3d000000, v16
	v_mul_f32_e32 v16, 0xbfb8aa3b, v16
	v_mul_f32_e32 v54, v54, v55
	v_mul_f32_e32 v56, 0x3d000000, v56
	v_exp_f32_e32 v55, v16
	v_and_b32_e32 v195, 0xffff0000, v17
	v_mul_f32_e32 v16, 0xbfb8aa3b, v194
	v_rcp_f32_e32 v159, v54
	v_exp_f32_e32 v54, v16
	v_mul_f32_e32 v16, 0xbfb8aa3b, v195
	v_mul_f32_e32 v17, 0xbfb8aa3b, v56
	v_exp_f32_e32 v16, v16
	v_exp_f32_e32 v17, v17
	v_rcp_f32_e32 v51, v51
	v_pk_add_f32 v[54:55], v[54:55], 1.0 op_sel_hi:[1,0]
	v_pk_mul_f32 v[200:201], v[8:9], v[14:15]
	v_pk_add_f32 v[16:17], v[16:17], 1.0 op_sel_hi:[1,0]
	v_mul_f32_e32 v54, v54, v55
	v_mul_f32_e32 v16, v16, v17
	v_rcp_f32_e32 v197, v16
	v_pk_mul_f32 v[16:17], v[6:7], v[52:53]
	v_rcp_f32_e32 v196, v54
	v_pk_mul_f32 v[198:199], v[16:17], v[50:51]
	ds_read_b128 v[14:17], v187
	ds_read_b128 v[50:53], v186
	ds_read_b128 v[54:57], v186 offset:16
	ds_read_b128 v[90:93], v187 offset:16
	v_pk_mul_f32 v[190:191], v[200:201], v[190:191]
	v_pk_mul_f32 v[192:193], v[2:3], v[192:193]
	s_waitcnt lgkmcnt(2)
	v_pk_add_f32 v[16:17], v[52:53], v[16:17]
	v_pk_add_f32 v[14:15], v[50:51], v[14:15]
	v_mul_f32_e32 v51, v17, v17
	v_mul_f32_e32 v50, v15, v15
	s_waitcnt lgkmcnt(0)
	v_pk_add_f32 v[52:53], v[54:55], v[90:91]
	v_fmac_f32_e32 v50, v14, v14
	v_fmac_f32_e32 v51, v16, v16
	v_add_f32_e32 v50, v50, v51
	v_mul_f32_e32 v51, v53, v53
	v_pk_add_f32 v[56:57], v[56:57], v[92:93]
	v_fmac_f32_e32 v51, v52, v52
	v_add_f32_e32 v50, v50, v51
	v_mul_f32_e32 v51, v57, v57
	v_fmac_f32_e32 v51, v56, v56
	v_add_f32_e32 v92, v51, v50
	ds_bpermute_b32 v93, v109, v92
	v_pk_mul_f32 v[50:51], v[4:5], v[194:195]
	v_pk_mul_f32 v[14:15], v[198:199], v[14:15]
	v_pk_mul_f32 v[90:91], v[50:51], v[196:197]
	v_cvt_pk_bf16_f32 v50, v14, v15
	s_waitcnt lgkmcnt(0)
	v_add_f32_e32 v92, v92, v93
	ds_bpermute_b32 v93, v160, v92
	v_pk_mul_f32 v[14:15], v[190:191], v[16:17]
	v_pk_mul_f32 v[54:55], v[192:193], v[158:159]
	v_cvt_pk_bf16_f32 v51, v14, v15
	v_pk_mul_f32 v[16:17], v[54:55], v[52:53]
	s_waitcnt lgkmcnt(0)
	v_add_f32_e32 v14, v92, v93
	ds_bpermute_b32 v15, v161, v14
	v_cvt_pk_bf16_f32 v52, v16, v17
	v_pk_mul_f32 v[16:17], v[90:91], v[56:57]
	s_nop 0
	v_cvt_pk_bf16_f32 v53, v16, v17
	global_store_dwordx4 v[142:143], v[50:53], off
	s_and_saveexec_b64 s[28:29], s[8:9]
	s_cbranch_execz .LBB0_553
	s_waitcnt lgkmcnt(0)
	v_add_f32_e32 v16, v14, v15
	v_lshl_add_u64 v[14:15], s[56:57], 0, v[144:145]
	global_store_dword v[14:15], v16, off

; #define LAS __attribute__((address_space(3)))
; __device__ __forceinline__ void p2b_gla_main(Frame& F) {
;     ...
;             bf16x8_t vf[2];
; #pragma unroll
;             for (int s = 0; s < 2; ++s) { const LAS unsigned char* vp = lds + L_V + (32 * s + 8 * g + q4) * VST + (16 * cw + 4 * p4) * 2; vf[s] = cat8(tr_read(vp), tr_read(vp + 4 * VST)); }
;             bf16x8_t sb[4];
; #pragma unroll
;             for (int s = 0; s < 4; ++s) { v4u t; t.x = cvtpk(S[2 * s][0], S[2 * s][1]); t.y = cvtpk(S[2 * s][2], S[2 * s][3]); t.z = cvtpk(S[2 * s + 1][0], S[2 * s + 1][1]); t.w = cvtpk(S[2 * s + 1][2], S[2 * s + 1][3]); sb[s] = __builtin_bit_cast(bf16x8_t, t); }
;             float gs[8];
; #pragma unroll
;             for (int j = 0; j < 4; ++j) { const unsigned wj = cgr[j]; const float x0 = bflo(wj), x1 = bfhi(wj);
;                 const unsigned wb_ = (j < 2) ? cgb.x : cgb.y; const int sh = 16 * (j & 1);
;                 const float b0 = ((float)((wb_ >> sh) & 0xffu) - 128.f) * 0.03125f, b1 = ((float)((wb_ >> (sh + 8)) & 0xffu) - 128.f) * 0.03125f;
;                 gs[2 * j] = gwv[2 * j] * x0 * __builtin_amdgcn_rcpf((1.0f + __builtin_amdgcn_exp2f(-1.4426950408889634f * x0)) * (1.0f + __builtin_amdgcn_exp2f(-1.4426950408889634f * b0)));
;                 gs[2 * j + 1] = gwv[2 * j + 1] * x1 * __builtin_amdgcn_rcpf((1.0f + __builtin_amdgcn_exp2f(-1.4426950408889634f * x1)) * (1.0f + __builtin_amdgcn_exp2f(-1.4426950408889634f * b1))); }
; #pragma unroll
;             for (int it = 0; it < 4; ++it) {
;                 f32x4 oa = {0.f, 0.f, 0.f, 0.f};
;                 { const bf16x8_t a = *(const LAS bf16x8_t*)(lds + L_ATT + (16 * it + c16) * AST + (32 * kh + 8 * g) * 2); oa = MFMA16(a, kh ? vf[1] : vf[0], oa); }
;                 const LAS unsigned char* qp = lds + L_QD + (16 * it + c16) * QST + (128 * kh) * 2 + g * 16;
; #pragma unroll
;                 for (int s = 0; s < 4; ++s) oa = MFMA16(*(const LAS bf16x8_t*)(qp + s * 64), sb[s], oa);
; #pragma unroll
;                 for (int r = 0; r < 4; ++r) *(LAS float*)(lds + L_OP + kh * 64 * OST + (16 * it + 4 * g + r) * OST + (16 * cw + c16) * 4) = oa[r];
;                 if (c + 1 < SEQ / GCHUNK) GLA_LOAD_QK(c + 1, it);
;             }
; #pragma unroll
;             for (int t = 0; t < 8; ++t) {
;                 const LAS unsigned char* kp = lds + L_KT + (128 * kh + 16 * t + c16) * KST + g * 16;
; #pragma unroll
.LBB0_555:
	ds_read_b64_tr_b16 v[54:55], v181
	ds_read_b64_tr_b16 v[56:57], v181 offset:576
	ds_read_b64_tr_b16 v[58:59], v181 offset:4608
	ds_read_b64_tr_b16 v[60:61], v181 offset:5184
	v_cvt_pk_bf16_f32 v14, v42, v43
	v_cvt_pk_bf16_f32 v15, v44, v45
	ds_read_b128 v[42:45], v182
	ds_read_b128 v[50:53], v184
	v_cvt_pk_bf16_f32 v16, v46, v47
	v_cvt_pk_bf16_f32 v17, v48, v49
	s_waitcnt lgkmcnt(2)
	v_cndmask_b32_e64 v49, v61, v57, s[6:7]
	v_cndmask_b32_e64 v48, v60, v56, s[6:7]
	v_cndmask_b32_e64 v47, v59, v55, s[6:7]
	v_cndmask_b32_e64 v46, v58, v54, s[6:7]
	ds_read_b128 v[54:57], v184 offset:64
	v_cvt_pk_bf16_f32 v34, v34, v35
	s_waitcnt lgkmcnt(2)
	v_mfma_f32_16x16x32_bf16 v[42:45], v[42:45], v[46:49], 0
	v_cvt_pk_bf16_f32 v35, v36, v37
	v_cvt_pk_bf16_f32 v36, v26, v27
	v_cvt_pk_bf16_f32 v37, v28, v29
	ds_read_b128 v[26:29], v184 offset:128
	s_waitcnt lgkmcnt(2)
	v_mfma_f32_16x16x32_bf16 v[42:45], v[50:53], v[14:17], v[42:45]
	ds_read_b128 v[50:53], v184 offset:192
	v_cvt_pk_bf16_f32 v30, v30, v31
	v_cvt_pk_bf16_f32 v31, v32, v33
	s_waitcnt lgkmcnt(2)
	v_mfma_f32_16x16x32_bf16 v[42:45], v[54:57], v[34:37], v[42:45]
	v_cvt_pk_bf16_f32 v32, v38, v39
	v_cvt_pk_bf16_f32 v33, v40, v41
	v_cvt_pk_bf16_f32 v18, v18, v19
	v_cvt_pk_bf16_f32 v19, v20, v21
	s_waitcnt lgkmcnt(1)
	v_mfma_f32_16x16x32_bf16 v[26:29], v[26:29], v[30:33], v[42:45]
	v_cvt_pk_bf16_f32 v20, v22, v23
	v_cvt_pk_bf16_f32 v21, v24, v25
	s_mul_i32 s10, s25, s23
	s_mul_hi_u32 s28, s25, s22
	s_waitcnt lgkmcnt(0)
	v_mfma_f32_16x16x32_bf16 v[22:25], v[50:53], v[18:21], v[26:29]
	s_nop 7
	ds_write2_b32 v185, v22, v23 offset1:68
	ds_write2_b32 v185, v24, v25 offset0:136 offset1:204
	ds_read_b128 v[22:25], v182 offset:2560
	ds_read_b128 v[26:29], v184 offset:8704
	ds_read_b128 v[38:41], v184 offset:8768
	ds_read_b128 v[42:45], v184 offset:8832
	s_waitcnt lgkmcnt(3)
	v_mfma_f32_16x16x32_bf16 v[22:25], v[22:25], v[46:49], 0
	v_add_u32_sdwa v50, v138, s65 dst_sel:DWORD dst_unused:UNUSED_PAD src0_sel:BYTE_0 src1_sel:DWORD
	s_add_i32 s29, s28, s10
	s_mul_i32 s28, s25, s22
	s_waitcnt lgkmcnt(2)
	v_mfma_f32_16x16x32_bf16 v[22:25], v[26:29], v[14:17], v[22:25]
	ds_read_b128 v[26:29], v184 offset:8896
	s_lshl_b64 s[28:29], s[28:29], 1
	s_add_u32 s10, s26, s28
	s_waitcnt lgkmcnt(2)
	v_mfma_f32_16x16x32_bf16 v[22:25], v[38:41], v[34:37], v[22:25]
	v_cvt_f32_i32_e32 v38, v50
	v_add_u32_sdwa v39, v138, s65 dst_sel:DWORD dst_unused:UNUSED_PAD src0_sel:BYTE_1 src1_sel:DWORD
	v_cvt_f32_i32_e32 v39, v39
	s_waitcnt lgkmcnt(1)
	v_mfma_f32_16x16x32_bf16 v[22:25], v[42:45], v[30:33], v[22:25]
	v_mul_f32_e32 v38, 0x3d000000, v38
	v_add_u32_sdwa v42, v138, s65 dst_sel:DWORD dst_unused:UNUSED_PAD src0_sel:BYTE_3 src1_sel:DWORD
	v_mul_f32_e32 v39, 0x3d000000, v39
	s_waitcnt lgkmcnt(0)
	v_mfma_f32_16x16x32_bf16 v[22:25], v[26:29], v[18:21], v[22:25]
	s_nop 7
	ds_write2_b32 v188, v22, v23 offset0:64 offset1:132
	ds_write2_b32 v189, v24, v25 offset0:72 offset1:140
	ds_read_b128 v[22:25], v182 offset:5120
	v_mul_f32_e32 v26, 0xbfb8aa3b, v38
	v_exp_f32_e32 v53, v26
	ds_read_b128 v[26:29], v184 offset:17408
	v_mul_f32_e32 v38, 0xbfb8aa3b, v39
	v_exp_f32_e32 v55, v38
	v_add_u32_sdwa v38, v138, s65 dst_sel:DWORD dst_unused:UNUSED_PAD src0_sel:BYTE_2 src1_sel:DWORD
	v_cvt_f32_i32_e32 v52, v38
	ds_read_b128 v[38:41], v184 offset:17472
	s_waitcnt lgkmcnt(2)
	v_mfma_f32_16x16x32_bf16 v[22:25], v[22:25], v[46:49], 0
	v_cvt_f32_i32_e32 v54, v42
	ds_read_b128 v[42:45], v184 offset:17536
	v_mul_f32_e32 v52, 0x3d000000, v52
	s_waitcnt lgkmcnt(2)
	v_mfma_f32_16x16x32_bf16 v[22:25], v[26:29], v[14:17], v[22:25]
	ds_read_b128 v[26:29], v184 offset:17600
	v_mul_f32_e32 v54, 0x3d000000, v54
	s_addc_u32 s27, s27, s29
	s_waitcnt lgkmcnt(2)
	v_mfma_f32_16x16x32_bf16 v[22:25], v[38:41], v[34:37], v[22:25]
	v_add_u32_sdwa v39, v139, s65 dst_sel:DWORD dst_unused:UNUSED_PAD src0_sel:BYTE_0 src1_sel:DWORD
	v_cvt_f32_i32_e32 v39, v39
	v_add_u32_sdwa v40, v139, s65 dst_sel:DWORD dst_unused:UNUSED_PAD src0_sel:BYTE_1 src1_sel:DWORD
	s_waitcnt lgkmcnt(1)
	v_mfma_f32_16x16x32_bf16 v[22:25], v[42:45], v[30:33], v[22:25]
	v_mul_f32_e32 v38, 0xbfb8aa3b, v52
	v_cvt_f32_i32_e32 v40, v40
	v_exp_f32_e32 v57, v38
	s_waitcnt lgkmcnt(0)
	v_mfma_f32_16x16x32_bf16 v[22:25], v[26:29], v[18:21], v[22:25]
	s_nop 7
	ds_write2_b32 v135, v22, v23 offset0:128 offset1:196
	ds_write2_b32 v137, v24, v25 offset0:8 offset1:76
	ds_read_b128 v[22:25], v182 offset:7680
	ds_read_b128 v[26:29], v184 offset:26112
	v_mul_f32_e32 v38, 0xbfb8aa3b, v54
	v_exp_f32_e32 v59, v38
	v_mul_f32_e32 v38, 0x3d000000, v39
	v_mul_f32_e32 v38, 0xbfb8aa3b, v38
	v_mul_f32_e32 v42, 0x3d000000, v40
	v_exp_f32_e32 v61, v38
	ds_read_b128 v[38:41], v184 offset:26176
	s_waitcnt lgkmcnt(2)
	v_mfma_f32_16x16x32_bf16 v[22:25], v[22:25], v[46:49], 0
	v_mul_f32_e32 v46, 0xbfb8aa3b, v42
	ds_read_b128 v[42:45], v184 offset:26240
	v_add_u32_sdwa v47, v139, s65 dst_sel:DWORD dst_unused:UNUSED_PAD src0_sel:BYTE_2 src1_sel:DWORD
	s_waitcnt lgkmcnt(2)
	v_mfma_f32_16x16x32_bf16 v[14:17], v[26:29], v[14:17], v[22:25]
	v_add_u32_sdwa v27, v139, s65 dst_sel:DWORD dst_unused:UNUSED_PAD src0_sel:BYTE_3 src1_sel:DWORD
	v_cvt_f32_i32_e32 v26, v47
	v_cvt_f32_i32_e32 v27, v27
	ds_read_b128 v[22:25], v184 offset:26304
	s_waitcnt lgkmcnt(2)
	v_mfma_f32_16x16x32_bf16 v[14:17], v[38:41], v[34:37], v[14:17]
	v_exp_f32_e32 v35, v46
	v_mul_f32_e32 v26, 0x3d000000, v26
	v_mul_f32_e32 v27, 0x3d000000, v27
	s_waitcnt lgkmcnt(1)
	v_mfma_f32_16x16x32_bf16 v[14:17], v[42:45], v[30:33], v[14:17]
	v_mul_f32_e32 v26, 0xbfb8aa3b, v26
	v_exp_f32_e32 v31, v26
	s_lshl_b32 s24, s24, 1
	s_waitcnt lgkmcnt(0)
	v_mfma_f32_16x16x32_bf16 v[14:17], v[22:25], v[18:21], v[14:17]
	s_nop 7
	ds_write2_b32 v131, v14, v15 offset0:64 offset1:132
	ds_write2_b32 v133, v16, v17 offset0:72 offset1:140
	s_waitcnt lgkmcnt(0)
	s_barrier
; #define LAS __attribute__((address_space(3)))
;     __device__ __forceinline__ float* SSQG() const { return (float*)(ws + WS_SSQG); }
; __device__ __forceinline__ void p2b_gla_main(Frame& F) {
;     ...
;             { const int row = tid >> 3, cg = tid & 7;
;                 const LAS f32x4* o0 = (const LAS f32x4*)(lds + L_OP + row * OST + cg * 32); const LAS f32x4* o1 = (const LAS f32x4*)(lds + L_OP + 64 * OST + row * OST + cg * 32);
;                 const f32x4 a = o0[0] + o1[0], bq = o0[1] + o1[1];
;                 v4u wv; wv.x = cvtpk(a[0] * gs[0], a[1] * gs[1]); wv.y = cvtpk(a[2] * gs[2], a[3] * gs[3]); wv.z = cvtpk(bq[0] * gs[4], bq[1] * gs[5]); wv.w = cvtpk(bq[2] * gs[6], bq[3] * gs[7]);
;                 const size_t grow = (size_t)c * GCHUNK + row;
;                 *(v4u*)(go0 + grow * gpitch + cg * 8) = wv;
;                 float ss = (a[0] * a[0] + a[1] * a[1]) + (a[2] * a[2] + a[3] * a[3]) + (bq[0] * bq[0] + bq[1] * bq[1]) + (bq[2] * bq[2] + bq[3] * bq[3]);
;                 ss += __shfl_xor(ss, 1); ss += __shfl_xor(ss, 2); ss += __shfl_xor(ss, 4);
;                 if (cg == 0) F.SSQG()[((size_t)b * SEQ + grow) * 32 + h * 8 + vs] = ss; }
	ds_read_b128 v[14:17], v187
	ds_read_b128 v[18:21], v186
	v_mul_f32_e32 v22, 0xbfb8aa3b, v27
	v_exp_f32_e32 v33, v22
	ds_read_b128 v[22:25], v187 offset:16
	ds_read_b128 v[26:29], v186 offset:16
	s_add_u32 s26, s10, s24
	s_waitcnt lgkmcnt(2)
	v_pk_add_f32 v[14:15], v[14:15], v[18:19]
	v_lshlrev_b32_e32 v18, 16, v10
	v_mul_f32_e32 v19, 0xbfb8aa3b, v18
	v_exp_f32_e32 v52, v19
	v_and_b32_e32 v19, 0xffff0000, v10
	v_mul_f32_e32 v10, 0xbfb8aa3b, v19
	v_exp_f32_e32 v54, v10
	v_pk_add_f32 v[16:17], v[16:17], v[20:21]
	v_pk_add_f32 v[20:21], v[52:53], 1.0 op_sel_hi:[1,0]
	v_pk_mul_f32 v[6:7], v[6:7], v[18:19]
	v_mul_f32_e32 v10, v20, v21
	v_pk_add_f32 v[36:37], v[54:55], 1.0 op_sel_hi:[1,0]
	v_rcp_f32_e32 v20, v10
	v_mul_f32_e32 v10, v36, v37
	v_rcp_f32_e32 v21, v10
	v_lshlrev_b32_e32 v10, 16, v11
	v_mul_f32_e32 v18, 0xbfb8aa3b, v10
	v_and_b32_e32 v11, 0xffff0000, v11
	v_exp_f32_e32 v56, v18
	v_mul_f32_e32 v18, 0xbfb8aa3b, v11
	v_exp_f32_e32 v58, v18
	v_pk_mul_f32 v[6:7], v[6:7], v[20:21]
	v_pk_add_f32 v[18:19], v[56:57], 1.0 op_sel_hi:[1,0]
	v_pk_mul_f32 v[6:7], v[6:7], v[14:15]
	v_pk_add_f32 v[20:21], v[58:59], 1.0 op_sel_hi:[1,0]
	v_pk_mul_f32 v[8:9], v[8:9], v[10:11]
	v_lshlrev_b32_e32 v10, 16, v12
	v_mul_f32_e32 v18, v18, v19
	v_mul_f32_e32 v19, v20, v21
	v_cvt_pk_bf16_f32 v6, v6, v7
	v_mul_f32_e32 v7, 0xbfb8aa3b, v10
	v_and_b32_e32 v11, 0xffff0000, v12
	v_rcp_f32_e32 v18, v18
	v_rcp_f32_e32 v19, v19
	v_exp_f32_e32 v60, v7
	v_mul_f32_e32 v7, 0xbfb8aa3b, v11
	v_exp_f32_e32 v34, v7
	v_pk_mul_f32 v[8:9], v[8:9], v[18:19]
	v_pk_add_f32 v[18:19], v[60:61], 1.0 op_sel_hi:[1,0]
	v_pk_mul_f32 v[8:9], v[8:9], v[16:17]
	v_mul_f32_e32 v7, v18, v19
	v_pk_add_f32 v[20:21], v[34:35], 1.0 op_sel_hi:[1,0]
	v_rcp_f32_e32 v18, v7
	v_mul_f32_e32 v7, v20, v21
	v_rcp_f32_e32 v19, v7
	v_pk_mul_f32 v[2:3], v[2:3], v[10:11]
	v_lshlrev_b32_e32 v10, 16, v13
	v_cvt_pk_bf16_f32 v7, v8, v9
	v_mul_f32_e32 v8, 0xbfb8aa3b, v10
	v_exp_f32_e32 v30, v8
	s_waitcnt lgkmcnt(0)
	v_pk_add_f32 v[22:23], v[22:23], v[26:27]
	v_pk_mul_f32 v[2:3], v[2:3], v[18:19]
	v_and_b32_e32 v11, 0xffff0000, v13
	v_pk_mul_f32 v[2:3], v[2:3], v[22:23]
	v_mul_f32_e32 v9, v17, v17
	v_cvt_pk_bf16_f32 v8, v2, v3
	v_pk_add_f32 v[2:3], v[30:31], 1.0 op_sel_hi:[1,0]
	v_fmac_f32_e32 v9, v16, v16
	v_mul_f32_e32 v2, v2, v3
	v_mul_f32_e32 v3, 0xbfb8aa3b, v11
	v_exp_f32_e32 v32, v3
	v_mul_f32_e32 v3, v15, v15
	v_fmac_f32_e32 v3, v14, v14
	v_add_f32_e32 v3, v3, v9
	v_mul_f32_e32 v9, v23, v23
	v_pk_add_f32 v[24:25], v[24:25], v[28:29]
	v_fmac_f32_e32 v9, v22, v22
	v_add_f32_e32 v3, v9, v3
	v_mul_f32_e32 v9, v25, v25
	v_fmac_f32_e32 v9, v24, v24
	v_add_f32_e32 v9, v9, v3
	ds_bpermute_b32 v14, v109, v9
	v_pk_add_f32 v[12:13], v[32:33], 1.0 op_sel_hi:[1,0]
	v_rcp_f32_e32 v2, v2
	v_mul_f32_e32 v3, v12, v13
	v_rcp_f32_e32 v3, v3
	v_pk_mul_f32 v[4:5], v[4:5], v[10:11]
	s_waitcnt lgkmcnt(0)
	v_add_f32_e32 v10, v9, v14
	ds_bpermute_b32 v11, v160, v10
	v_pk_mul_f32 v[2:3], v[4:5], v[2:3]
	s_addc_u32 s27, s27, 0
	v_pk_mul_f32 v[2:3], v[2:3], v[24:25]
	v_mul_u32_u24_e32 v4, s25, v102
	v_cvt_pk_bf16_f32 v9, v2, v3
	s_waitcnt lgkmcnt(0)
	v_add_f32_e32 v2, v10, v11
	ds_bpermute_b32 v3, v161, v2
	v_lshl_add_u64 v[50:51], s[26:27], 0, v[96:97]
	v_lshlrev_b32_e32 v4, 1, v4
	v_mov_b32_e32 v5, v97
	v_lshl_add_u64 v[4:5], v[50:51], 0, v[4:5]
	global_store_dwordx4 v[4:5], v[6:9], off
	s_and_saveexec_b64 s[24:25], s[8:9]
	s_cbranch_execz .LBB0_541
	s_waitcnt lgkmcnt(0)
	v_add_f32_e32 v4, v2, v3
	v_lshl_add_u64 v[2:3], s[22:23], 0, v[102:103]
	v_lshlrev_b64 v[2:3], 7, v[2:3]
	v_lshl_add_u64 v[2:3], s[12:13], 0, v[2:3]
	s_lshl_b32 s10, s75, 5
	v_lshl_add_u64 v[2:3], v[2:3], 0, s[10:11]
	s_lshl_b32 s10, s74, 2
	v_lshl_add_u64 v[2:3], v[2:3], 0, s[10:11]
	global_store_dword v[2:3], v4, off
	s_branch .LBB0_541

; __global__ void __launch_bounds__(NTHREADS, 2) hybrid_fwd(Args args) {
	.amdhsa_kernel _Z10hybrid_fwd4Args
		.amdhsa_group_segment_fixed_size 0
		.amdhsa_private_segment_fixed_size 0
		.amdhsa_kernarg_size 384
		.amdhsa_user_sgpr_count 2
		.amdhsa_user_sgpr_dispatch_ptr 0
		.amdhsa_user_sgpr_queue_ptr 0
		.amdhsa_user_sgpr_kernarg_segment_ptr 1
		.amdhsa_user_sgpr_dispatch_id 0
		.amdhsa_user_sgpr_kernarg_preload_length 0
		.amdhsa_user_sgpr_kernarg_preload_offset 0
		.amdhsa_user_sgpr_private_segment_size 0
		.amdhsa_uses_dynamic_stack 0
		.amdhsa_enable_private_segment 0
		.amdhsa_system_sgpr_workgroup_id_x 1
		.amdhsa_system_sgpr_workgroup_id_y 0
		.amdhsa_system_sgpr_workgroup_id_z 0
		.amdhsa_system_sgpr_workgroup_info 0
		.amdhsa_system_vgpr_workitem_id 0
		.amdhsa_next_free_vgpr 253
		.amdhsa_next_free_sgpr 102
		.amdhsa_accum_offset 256
		.amdhsa_reserve_vcc 1
		.amdhsa_float_round_mode_32 0
		.amdhsa_float_round_mode_16_64 0
		.amdhsa_float_denorm_mode_32 3
		.amdhsa_float_denorm_mode_16_64 3
		.amdhsa_dx10_clamp 1
		.amdhsa_ieee_mode 1
		.amdhsa_fp16_overflow 0
		.amdhsa_tg_split 0
		.amdhsa_exception_fp_ieee_invalid_op 0
		.amdhsa_exception_fp_denorm_src 0
		.amdhsa_exception_fp_ieee_div_zero 0
		.amdhsa_exception_fp_ieee_overflow 0
		.amdhsa_exception_fp_ieee_underflow 0
		.amdhsa_exception_fp_ieee_inexact 0
		.amdhsa_exception_int_div_zero 0
	.end_amdhsa_kernel

; __global__ void __launch_bounds__(NTHREADS, 2) hybrid_fwd(Args args) {
amdhsa.kernels:
  - .agpr_count:     0
    .args:
      - .offset:         0
        .size:           128
        .value_kind:     by_value
      - .offset:         128
        .size:           4
        .value_kind:     hidden_block_count_x
      - .offset:         132
        .size:           4
        .value_kind:     hidden_block_count_y
      - .offset:         136
        .size:           4
        .value_kind:     hidden_block_count_z
      - .offset:         140
        .size:           2
        .value_kind:     hidden_group_size_x
      - .offset:         142
        .size:           2
        .value_kind:     hidden_group_size_y
      - .offset:         144
        .size:           2
        .value_kind:     hidden_group_size_z
      - .offset:         146
        .size:           2
        .value_kind:     hidden_remainder_x
      - .offset:         148
        .size:           2
        .value_kind:     hidden_remainder_y
      - .offset:         150
        .size:           2
        .value_kind:     hidden_remainder_z
      - .offset:         168
        .size:           8
        .value_kind:     hidden_global_offset_x
      - .offset:         176
        .size:           8
        .value_kind:     hidden_global_offset_y
      - .offset:         184
        .size:           8
        .value_kind:     hidden_global_offset_z
      - .offset:         192
        .size:           2
        .value_kind:     hidden_grid_dims
      - .offset:         248
        .size:           4
        .value_kind:     hidden_dynamic_lds_size
    .group_segment_fixed_size: 0
    .kernarg_segment_align: 8
    .kernarg_segment_size: 384
    .language:       OpenCL C
    .language_version:
      - 2
      - 0
    .max_flat_workgroup_size: 512
    .name:           _Z10hybrid_fwd4Args
    .private_segment_fixed_size: 0
    .sgpr_count:     108
    .sgpr_spill_count: 14
    .symbol:         _Z10hybrid_fwd4Args.kd
    .uniform_work_group_size: 1
    .uses_dynamic_stack: false
    .vgpr_count:     253
    .vgpr_spill_count: 0
    .wavefront_size: 64
